# P0: DFT table built from one LDS-resident row (row k1=1) by gathers instead of evaluating sincos for every entry (bit-identical)
# speedup vs baseline: 1.0009x; 1.0009x over previous
; __device__ __forceinline__ unsigned pk2(float lo, float hi) { return pk2hw(lo, hi); }
; __global__ void __launch_bounds__(NTHR, 2) fwd_kernel(Args a) {
;     ...
;         for (int gi = gtid; gi < 2048 * 512; gi += NT) {
;             const int k1 = gi >> 9, j0 = (gi & 511) * 8; float v[8];
; #pragma unroll
;             for (int e = 0; e < 8; ++e) { const int j = j0 + e; const int ph = (k1 * (j & 2047)) & 2047; const float x = (float)ph * (1.0f / 1024.0f); v[e] = j < 2048 ? cospif(x) : -sinpif(x); }
;             u32x4 o; o.x = pk2(v[0], v[1]); o.y = pk2(v[2], v[3]); o.z = pk2(v[4], v[5]); o.w = pk2(v[6], v[7]);
;             *(u32x4*)(DT + (size_t)k1 * 4096 + j0) = o;
;         }
.LBB0_27:
	s_or_b64 exec, exec, s[2:3]
	s_waitcnt lgkmcnt(0)
	s_barrier
	s_add_u32 s72, s66, 0x7400000
	s_mov_b32 s1, 0x100000
	s_addc_u32 s73, s67, 0
	v_cmp_gt_i32_e32 vcc, s1, v4
	s_and_saveexec_b64 s[6:7], vcc
	s_cbranch_execz .LBB0_62
	v_add_u32_e32 v5, 0x1000, v10
	v_lshlrev_b32_e32 v30, 1, v10
	s_lshl_b32 s1, s86, 12
	s_mov_b64 s[8:9], 0
	s_movk_i32 s14, 0x7ff
	s_mov_b32 s15, 0x7f800000
	v_mov_b32_e32 v6, 0xbf1f24be
	v_mov_b32_e32 v7, 0x3e642e9d
	s_brev_b32 s16, 1
	v_mov_b32_e32 v1, 0
	s_mov_b32 s17, 0
	v_mov_b32_e32 v8, 0xffc00000
	v_mov_b32_e32 v9, 0x7fc00000
	v_add_u32_e32 v11, 0x200, v189
	s_branch .LBB0_30
.LBB0_29:
	s_or_b64 exec, exec, s[4:5]
	v_cvt_pk_bf16_f32 v12, v3, v12
	v_ashrrev_i32_e32 v3, 31, v2
	v_lshlrev_b64 v[2:3], 13, v[2:3]
	v_add_u32_e32 v11, s0, v11
	v_lshl_add_u64 v[2:3], s[72:73], 0, v[2:3]
	v_lshlrev_b32_e32 v0, 1, v0
	v_cmp_lt_i32_e32 vcc, s17, v11
	v_cvt_pk_bf16_f32 v13, v13, v14
	v_cvt_pk_bf16_f32 v14, v15, v16
	v_cvt_pk_bf16_f32 v15, v17, v22
	v_lshl_add_u64 v[2:3], v[2:3], 0, v[0:1]
	s_or_b64 s[8:9], vcc, s[8:9]
	v_add_u32_e32 v5, s1, v5
	ds_write_b128 v30, v[12:15]
	s_andn2_b64 exec, exec, s[8:9]
	s_cbranch_execz .LBB0_62

; __device__ __forceinline__ unsigned pk2(float lo, float hi) { return pk2hw(lo, hi); }
; __global__ void __launch_bounds__(NTHR, 2) fwd_kernel(Args a) {
;     ...
;         for (int gi = gtid; gi < 2048 * 512; gi += NT) {
;             const int k1 = gi >> 9, j0 = (gi & 511) * 8; float v[8];
; #pragma unroll
;             for (int e = 0; e < 8; ++e) { const int j = j0 + e; const int ph = (k1 * (j & 2047)) & 2047; const float x = (float)ph * (1.0f / 1024.0f); v[e] = j < 2048 ? cospif(x) : -sinpif(x); }
;             u32x4 o; o.x = pk2(v[0], v[1]); o.y = pk2(v[2], v[3]); o.z = pk2(v[4], v[5]); o.w = pk2(v[6], v[7]);
;             *(u32x4*)(DT + (size_t)k1 * 4096 + j0) = o;
;         }
.LBB0_62:
	s_or_b64 exec, exec, s[6:7]
	s_waitcnt lgkmcnt(0)
	s_barrier
	v_mov_b32_e32 v26, v4
	v_mov_b32_e32 v27, 0
	s_mov_b32 s98, 4
.Ldtg_loop:
	v_lshrrev_b32_e32 v28, 9, v26
	v_and_b32_e32 v29, 0x1ff, v26
	v_lshlrev_b32_e32 v29, 3, v29
	v_and_b32_e32 v31, 0x800, v29
	v_lshlrev_b32_e32 v31, 1, v31
	v_and_b32_e32 v32, 0x7ff, v29
	v_mul_u32_u24_e32 v32, v32, v28
	v_and_b32_e32 v32, 0x7ff, v32
	v_lshl_add_u32 v34, v32, 1, v31
	v_add_u32_e32 v32, v32, v28
	v_and_b32_e32 v32, 0x7ff, v32
	v_lshl_add_u32 v35, v32, 1, v31
	v_add_u32_e32 v32, v32, v28
	v_and_b32_e32 v32, 0x7ff, v32
	v_lshl_add_u32 v36, v32, 1, v31
	v_add_u32_e32 v32, v32, v28
	v_and_b32_e32 v32, 0x7ff, v32
	v_lshl_add_u32 v37, v32, 1, v31
	v_add_u32_e32 v32, v32, v28
	v_and_b32_e32 v32, 0x7ff, v32
	v_lshl_add_u32 v38, v32, 1, v31
	v_add_u32_e32 v32, v32, v28
	v_and_b32_e32 v32, 0x7ff, v32
	v_lshl_add_u32 v39, v32, 1, v31
	v_add_u32_e32 v32, v32, v28
	v_and_b32_e32 v32, 0x7ff, v32
	v_lshl_add_u32 v40, v32, 1, v31
	v_add_u32_e32 v32, v32, v28
	v_and_b32_e32 v32, 0x7ff, v32
	v_lshl_add_u32 v41, v32, 1, v31
	ds_read_u16 v42, v34
	ds_read_u16 v43, v35
	ds_read_u16 v44, v36
	ds_read_u16 v45, v37
	ds_read_u16 v46, v38
	ds_read_u16 v47, v39
	ds_read_u16 v48, v40
	ds_read_u16 v49, v41
	v_lshlrev_b64 v[50:51], 4, v[26:27]
	v_lshl_add_u64 v[50:51], s[72:73], 0, v[50:51]
	s_waitcnt lgkmcnt(0)
	v_lshl_or_b32 v52, v43, 16, v42
	v_lshl_or_b32 v53, v45, 16, v44
	v_lshl_or_b32 v54, v47, 16, v46
	v_lshl_or_b32 v55, v49, 16, v48
	global_store_dwordx4 v[50:51], v[52:55], off sc1
	v_add_u32_e32 v26, s0, v26
	s_sub_u32 s98, s98, 1
	s_cmp_lg_u32 s98, 0
	s_cbranch_scc1 .Ldtg_loop
	s_add_u32 s6, s66, 0x8400000
	s_movk_i32 s1, 0x4000
	s_addc_u32 s7, s67, 0
	v_cmp_gt_i32_e32 vcc, s1, v4
	s_and_saveexec_b64 s[4:5], vcc
	s_cbranch_execz .LBB0_97
	v_lshl_add_u32 v5, s88, 12, v10
	s_lshl_b32 s1, s86, 12
	s_mov_b64 s[8:9], 0
	s_movk_i32 s14, 0xff
	s_mov_b32 s15, 0x7f800000
	v_mov_b32_e32 v6, 0xbf1f24be
	v_mov_b32_e32 v7, 0x3e642e9d
	s_brev_b32 s16, 1
	v_mov_b32_e32 v1, 0
	s_movk_i32 s17, 0x3fff
	v_mov_b32_e32 v8, 0x7fc00000
	s_branch .LBB0_65
